# SWA unit: gate and sink loads of the epilogue issued at unit start
# baseline (speedup 1.0000x reference)
.LBB0_568:
	s_lshl_b32 s8, s0, 7
	s_add_u32 s10, s25, s8
	s_addc_u32 s11, s26, 0
	s_lshl_b32 s0, s0, 2
	v_mov_b32_e32 v0, s0
	v_lshlrev_b64 v[34:35], 11, v[110:111]
	v_lshl_add_u64 v[34:35], s[10:11], 0, v[34:35]
	v_mov_b32_e32 v109, v1
	v_lshl_add_u64 v[34:35], v[34:35], 0, v[108:109]
	v_mov_b32_e32 v46, v107
	s_nop 1
	v_permlane32_swap_b32_e32 v107, v46
	v_lshlrev_b64 v[44:45], 12, v[110:111]
	v_add_f32_e32 v56, v107, v46
	s_mov_b32 s9, s1
	v_lshl_add_u64 v[44:45], s[54:55], 0, v[44:45]
	v_lshl_add_u64 v[44:45], v[44:45], 0, s[8:9]
	v_mov_b32_e32 v99, v1
	v_lshl_add_u64 v[44:45], v[44:45], 0, v[98:99]
	v_lshl_add_u64 v[46:47], v[44:45], 0, s[6:7]
	v_add_co_u32_e32 v44, vcc, s42, v44
	s_add_i32 s43, s43, s34
	s_nop 0
	v_addc_co_u32_e32 v45, vcc, 0, v45, vcc
	s_cmpk_lt_i32 s43, 0x200
	s_waitcnt vmcnt(4)
	v_fma_f32 v0, v186, s39, -v130
	v_exp_f32_e32 v0, v0
	s_waitcnt vmcnt(3)
	v_lshlrev_b32_e32 v48, 16, v170
	v_and_b32_e32 v49, 0xffff0000, v170
	v_lshlrev_b32_e32 v36, 16, v171
	v_add_f32_e32 v0, v56, v0
	v_div_scale_f32 v56, s[8:9], v0, v0, 1.0
	v_rcp_f32_e32 v57, v56
	v_div_scale_f32 v58, vcc, 1.0, v0, 1.0
	v_and_b32_e32 v37, 0xffff0000, v171
	v_fma_f32 v59, -v56, v57, 1.0
	v_fmac_f32_e32 v57, v59, v57
	v_mul_f32_e32 v59, v58, v57
	v_fma_f32 v60, -v56, v59, v58
	v_fmac_f32_e32 v59, v60, v57
	v_fma_f32 v56, -v56, v59, v58
	v_div_fmas_f32 v56, v56, v57, v59
	v_div_fixup_f32 v0, v56, v0, 1.0
	s_waitcnt vmcnt(2)
	v_lshlrev_b32_e32 v50, 16, v172
	v_and_b32_e32 v51, 0xffff0000, v172
	v_lshlrev_b32_e32 v38, 16, v173
	v_and_b32_e32 v39, 0xffff0000, v173
	v_pk_mul_f32 v[2:3], v[2:3], v[0:1] op_sel_hi:[1,0]
	v_pk_mul_f32 v[4:5], v[4:5], v[0:1] op_sel_hi:[1,0]
	v_pk_mul_f32 v[6:7], v[6:7], v[0:1] op_sel_hi:[1,0]
	v_pk_mul_f32 v[8:9], v[8:9], v[0:1] op_sel_hi:[1,0]
	s_waitcnt vmcnt(1)
	v_lshlrev_b32_e32 v52, 16, v174
	v_and_b32_e32 v53, 0xffff0000, v174
	v_lshlrev_b32_e32 v40, 16, v175
	v_and_b32_e32 v41, 0xffff0000, v175
	s_waitcnt vmcnt(0)
	v_lshlrev_b32_e32 v54, 16, v176
	v_and_b32_e32 v55, 0xffff0000, v176
	v_lshlrev_b32_e32 v42, 16, v177
	v_and_b32_e32 v43, 0xffff0000, v177
	v_pk_mul_f32 v[10:11], v[10:11], v[0:1] op_sel_hi:[1,0]
	v_pk_mul_f32 v[12:13], v[12:13], v[0:1] op_sel_hi:[1,0]
	v_pk_mul_f32 v[14:15], v[14:15], v[0:1] op_sel_hi:[1,0]
	v_pk_mul_f32 v[16:17], v[16:17], v[0:1] op_sel_hi:[1,0]
	v_pk_mul_f32 v[2:3], v[2:3], v[48:49]
	v_pk_mul_f32 v[4:5], v[4:5], v[36:37]
	v_pk_mul_f32 v[6:7], v[6:7], v[50:51]
	v_pk_mul_f32 v[8:9], v[8:9], v[38:39]
	v_pk_mul_f32 v[10:11], v[10:11], v[52:53]
	v_pk_mul_f32 v[12:13], v[12:13], v[40:41]
	v_pk_mul_f32 v[14:15], v[14:15], v[54:55]
	v_pk_mul_f32 v[16:17], v[16:17], v[42:43]
	v_cvt_pk_bf16_f32 v2, v2, v3
	v_cvt_pk_bf16_f32 v3, v4, v5
	v_cvt_pk_bf16_f32 v4, v6, v7
	v_cvt_pk_bf16_f32 v5, v8, v9
	v_cvt_pk_bf16_f32 v6, v10, v11
	v_cvt_pk_bf16_f32 v7, v12, v13
	v_cvt_pk_bf16_f32 v8, v14, v15
	v_cvt_pk_bf16_f32 v9, v16, v17
	v_permlane32_swap_b32_e32 v2, v4
	v_permlane32_swap_b32_e32 v3, v5
	v_permlane32_swap_b32_e32 v6, v8
	v_permlane32_swap_b32_e32 v7, v9
	global_store_dwordx4 v[44:45], v[2:5], off offset:2048
	global_store_dwordx4 v[46:47], v[6:9], off offset:32
	s_nop 0
	v_pk_mul_f32 v[10:11], v[18:19], v[0:1] op_sel_hi:[1,0]
	v_pk_mul_f32 v[12:13], v[20:21], v[0:1] op_sel_hi:[1,0]
	v_pk_mul_f32 v[14:15], v[22:23], v[0:1] op_sel_hi:[1,0]
	v_pk_mul_f32 v[16:17], v[24:25], v[0:1] op_sel_hi:[1,0]
	v_pk_mul_f32 v[18:19], v[26:27], v[0:1] op_sel_hi:[1,0]
	v_pk_mul_f32 v[20:21], v[28:29], v[0:1] op_sel_hi:[1,0]
	v_pk_mul_f32 v[22:23], v[30:31], v[0:1] op_sel_hi:[1,0]
	v_pk_mul_f32 v[24:25], v[32:33], v[0:1] op_sel_hi:[1,0]
	s_waitcnt vmcnt(3)
	v_lshlrev_b32_e32 v26, 16, v178
	v_and_b32_e32 v27, 0xffff0000, v178
	v_lshlrev_b32_e32 v2, 16, v179
	v_and_b32_e32 v3, 0xffff0000, v179
	s_waitcnt vmcnt(2)
	v_lshlrev_b32_e32 v28, 16, v180
	v_and_b32_e32 v29, 0xffff0000, v180
	v_lshlrev_b32_e32 v4, 16, v181
	v_and_b32_e32 v5, 0xffff0000, v181
	s_waitcnt vmcnt(1)
	v_lshlrev_b32_e32 v30, 16, v182
	v_and_b32_e32 v31, 0xffff0000, v182
	v_lshlrev_b32_e32 v6, 16, v183
	v_and_b32_e32 v7, 0xffff0000, v183
	s_waitcnt vmcnt(0)
	v_lshlrev_b32_e32 v32, 16, v184
	v_and_b32_e32 v33, 0xffff0000, v184
	v_lshlrev_b32_e32 v8, 16, v185
	v_and_b32_e32 v9, 0xffff0000, v185
	v_pk_mul_f32 v[10:11], v[10:11], v[26:27]
	v_pk_mul_f32 v[12:13], v[12:13], v[2:3]
	v_pk_mul_f32 v[14:15], v[14:15], v[28:29]
	v_pk_mul_f32 v[16:17], v[16:17], v[4:5]
	v_pk_mul_f32 v[18:19], v[18:19], v[30:31]
	v_pk_mul_f32 v[20:21], v[20:21], v[6:7]
	v_pk_mul_f32 v[22:23], v[22:23], v[32:33]
	v_pk_mul_f32 v[24:25], v[24:25], v[8:9]
	v_cvt_pk_bf16_f32 v2, v10, v11
	v_cvt_pk_bf16_f32 v3, v12, v13
	v_cvt_pk_bf16_f32 v4, v14, v15
	v_cvt_pk_bf16_f32 v5, v16, v17
	v_cvt_pk_bf16_f32 v6, v18, v19
	v_cvt_pk_bf16_f32 v7, v20, v21
	v_cvt_pk_bf16_f32 v8, v22, v23
	v_cvt_pk_bf16_f32 v9, v24, v25
	v_permlane32_swap_b32_e32 v2, v4
	v_permlane32_swap_b32_e32 v3, v5
	v_permlane32_swap_b32_e32 v6, v8
	v_permlane32_swap_b32_e32 v7, v9
	global_store_dwordx4 v[46:47], v[2:5], off offset:64
	global_store_dwordx4 v[46:47], v[6:9], off offset:96
	s_cbranch_scc0 .LBB0_584
.LBB0_569:
	s_and_b32 s0, s43, 7
	v_readfirstlane_b32 s12, v168
	s_lshr_b32 s8, s12, 8
	s_lshl_b32 s0, s0, 1
	s_add_i32 s0, s8, s0
	s_ashr_i32 s44, s43, 3
	s_lshr_b32 s13, s12, 6
	s_lshl_b64 s[8:9], s[0:1], 20
	s_add_u32 s10, s5, s8
	s_addc_u32 s11, s18, s9
	s_lshl_b32 s8, s43, 19
	s_and_b32 s14, s8, 0x300000
	s_add_u32 s8, s19, s14
	s_addc_u32 s9, s22, 0
	s_lshr_b32 s16, s12, 1
	s_lshl_b32 s15, s44, 7
	s_and_b32 s16, s16, 0x60
	s_or_b32 s45, s16, s15
	v_or_b32_e32 v110, s45, v119
	v_ashrrev_i32_e32 v111, 31, v110
	v_lshlrev_b64 v[2:3], 7, v[110:111]
	v_lshl_add_u64 v[2:3], s[10:11], 0, v[2:3]
	v_lshl_add_u64 v[2:3], v[2:3], 0, v[100:101]
	global_load_dwordx4 v[66:69], v[2:3], off
	global_load_dwordx4 v[70:73], v[2:3], off offset:32
	global_load_dwordx4 v[74:77], v[2:3], off offset:64
	global_load_dwordx4 v[78:81], v[2:3], off offset:96
	s_lshl_b32 s91, s0, 7
	s_add_u32 s92, s25, s91
	s_addc_u32 s93, s26, 0
	v_lshlrev_b64 v[188:189], 11, v[110:111]
	v_lshl_add_u64 v[188:189], s[92:93], 0, v[188:189]
	v_mov_b32_e32 v190, v108
	v_mov_b32_e32 v191, 0
	v_lshl_add_u64 v[188:189], v[188:189], 0, v[190:191]
	global_load_dwordx2 v[170:171], v[188:189], off
	global_load_dwordx2 v[172:173], v[188:189], off offset:16
	global_load_dwordx2 v[174:175], v[188:189], off offset:32
	global_load_dwordx2 v[176:177], v[188:189], off offset:48
	global_load_dwordx2 v[178:179], v[188:189], off offset:64
	global_load_dwordx2 v[180:181], v[188:189], off offset:80
	global_load_dwordx2 v[182:183], v[188:189], off offset:96
	global_load_dwordx2 v[184:185], v[188:189], off offset:112
	s_lshl_b32 s91, s0, 2
	v_mov_b32_e32 v187, s91
	global_load_dword v186, v187, s[48:49]
	s_add_u32 s10, s23, s14
	s_addc_u32 s11, s24, 0
	s_max_i32 s47, s44, 1
	s_lshr_b32 s12, s12, 5
	v_lshl_or_b32 v0, s13, 7, v118
	s_add_i32 s47, s47, -1
	s_or_b32 s12, s12, 1
	v_lshrrev_b32_e32 v109, 3, v0
	s_lshl_b32 s15, s47, 7
	v_lshl_or_b32 v2, s12, 6, v118
	v_add_u32_e32 v0, s15, v109
	v_lshrrev_b32_e32 v129, 3, v2
	v_lshrrev_b32_e32 v4, 4, v2
	v_lshlrev_b64 v[2:3], 7, v[0:1]
	v_xor_b32_e32 v8, v4, v168
	v_add_u32_e32 v0, s15, v129
	s_lshl_b32 s46, s13, 11
	v_lshl_add_u64 v[4:5], s[10:11], 0, v[2:3]
	v_lshlrev_b64 v[6:7], 7, v[0:1]
	v_lshlrev_b32_e32 v0, 3, v8
	s_add_i32 s13, s46, 0
	v_lshl_add_u64 v[2:3], s[8:9], 0, v[2:3]
	v_lshl_add_u64 v[4:5], v[4:5], 0, v[102:103]
	v_and_b32_e32 v0, 56, v0
	s_mov_b32 s15, m0
	s_mov_b32 m0, s13
	s_nop 0
	global_load_lds_dwordx4 v[4:5], off
	s_mov_b32 m0, s15
	s_add_i32 s14, s46, s27
	s_lshl_b32 s50, s12, 10
	v_lshl_add_u64 v[2:3], v[2:3], 0, v[104:105]
	v_lshl_add_u64 v[8:9], s[10:11], 0, v[6:7]
	v_lshlrev_b32_e32 v0, 1, v0
	s_mov_b32 s13, m0
	s_mov_b32 m0, s14
	s_nop 0
	global_load_lds_dwordx4 v[2:3], off
	s_mov_b32 m0, s13
	s_add_i32 s12, s50, 0
	v_lshl_add_u64 v[6:7], s[8:9], 0, v[6:7]
	v_lshl_add_u64 v[2:3], v[8:9], 0, v[0:1]
	s_mov_b32 s13, m0
	s_mov_b32 m0, s12
	s_nop 0
	global_load_lds_dwordx4 v[2:3], off
	s_mov_b32 m0, s13
	s_add_i32 s16, s50, s27
	v_lshl_add_u64 v[4:5], v[6:7], 0, v[104:105]
	s_mov_b32 s12, m0
	s_mov_b32 m0, s16
	s_nop 0
	global_load_lds_dwordx4 v[4:5], off
	s_mov_b32 m0, s12
	s_waitcnt vmcnt(0) lgkmcnt(0)
	s_barrier
	s_cmp_gt_i32 s47, s44
	s_waitcnt vmcnt(3)
	s_waitcnt vmcnt(2)
	s_waitcnt vmcnt(1)
	s_waitcnt vmcnt(0)
	s_cbranch_scc1 .LBB0_567
	s_add_i32 s12, s0, 1
	v_cvt_f32_u32_e32 v3, s12
	v_lshlrev_b32_e32 v2, 1, v96
	v_mov_b32_e32 v5, v1
	v_mov_b32_e32 v6, v1
	v_mul_f32_e32 v3, 0xc1000000, v3
	v_mul_f32_e32 v4, 0x3d800000, v3
	v_cmp_gt_f32_e32 vcc, s38, v4
	s_and_b64 s[12:13], vcc, exec
	s_cselect_b32 s12, 0xffffffc0, 0
	v_cndmask_b32_e32 v4, 0, v127, vcc
	v_fmac_f32_e32 v4, 0x3d800000, v3
	v_exp_f32_e32 v3, v4
	v_mov_b32_e32 v7, v1
	v_mov_b32_e32 v8, v1
	v_mov_b32_e32 v9, v1
	v_ldexp_f32 v3, v3, s12
	v_mul_f32_e32 v4, 0x3fb8aa3b, v3
	v_mov_b32_e32 v3, v1
	v_lshl_add_u64 v[114:115], s[8:9], 0, v[2:3]
	v_readfirstlane_b32 s8, v4
	v_mov_b32_e32 v2, v1
	v_mov_b32_e32 v4, v1
	v_mov_b32_e32 v10, v1
	v_mov_b32_e32 v11, v1
	v_mov_b32_e32 v12, v1
	v_mov_b32_e32 v13, v1
	v_mov_b32_e32 v14, v1
	v_mov_b32_e32 v15, v1
	v_mov_b32_e32 v16, v1
	v_mov_b32_e32 v17, v1
	v_mov_b32_e32 v18, v1
	v_mov_b32_e32 v19, v1
	v_mov_b32_e32 v20, v1
	v_mov_b32_e32 v21, v1
	v_mov_b32_e32 v22, v1
	v_mov_b32_e32 v23, v1
	v_mov_b32_e32 v24, v1
	v_mov_b32_e32 v25, v1
	v_mov_b32_e32 v26, v1
	v_mov_b32_e32 v27, v1
	v_mov_b32_e32 v28, v1
	v_mov_b32_e32 v29, v1
	v_mov_b32_e32 v30, v1
	v_mov_b32_e32 v31, v1
	v_mov_b32_e32 v107, v1
	v_lshl_add_u64 v[116:117], s[10:11], 0, v[0:1]
	v_mov_b32_e32 v0, v1
	v_mov_b64_e32 v[32:33], v[30:31]
	v_lshl_add_u64 v[112:113], s[10:11], 0, v[106:107]
	s_mov_b32 s9, s8
	s_mov_b32 s51, s8
	s_mov_b32 s62, s8
	s_mov_b32 s63, s8
	s_mov_b32 s64, s8
	s_mov_b32 s65, s8
	s_mov_b32 s66, s8
	s_mov_b32 s67, s8
	s_mov_b32 s68, s8
	s_mov_b32 s69, s8
	s_mov_b32 s70, s8
	s_mov_b32 s71, s8
	s_mov_b32 s72, s8
	s_mov_b32 s73, s8
	s_mov_b32 s74, s8
	v_mov_b32_e32 v130, 0xe0ad78ec
	v_mov_b32_e32 v107, 0
	s_mov_b32 s75, s47
	v_mov_b64_e32 v[30:31], v[28:29]
	v_mov_b64_e32 v[28:29], v[26:27]
	v_mov_b64_e32 v[26:27], v[24:25]
	v_mov_b64_e32 v[24:25], v[22:23]
	v_mov_b64_e32 v[22:23], v[20:21]
	v_mov_b64_e32 v[20:21], v[18:19]
	v_mov_b64_e32 v[18:19], v[16:17]
	v_mov_b64_e32 v[16:17], v[14:15]
	v_mov_b64_e32 v[14:15], v[12:13]
	v_mov_b64_e32 v[12:13], v[10:11]
	v_mov_b64_e32 v[10:11], v[8:9]
	v_mov_b64_e32 v[8:9], v[6:7]
	v_mov_b64_e32 v[6:7], v[4:5]
	v_mov_b64_e32 v[4:5], v[2:3]
	v_mov_b64_e32 v[2:3], v[0:1]
	s_branch .LBB0_572
